# grid barrier followers issue their cache invalidate right after arriving (overlapped with the wait); the XCC leader completes its invalidate before releasing its XCC
# speedup vs baseline: 1.0508x; 1.0025x over previous
; #define GSYNC() do { ++bar_n; grid_barrier(bar_ctr, bar_n * (unsigned)G); } while (0)
; __device__ __forceinline__ void grid_barrier(unsigned* ctr, unsigned target) {
;     asm volatile("s_waitcnt vmcnt(0)" ::: "memory");
;     __syncthreads();
;     if (threadIdx.x == 0) {
;         __builtin_amdgcn_fence(__ATOMIC_RELEASE, "agent");
;         asm volatile("s_waitcnt vmcnt(0)" ::: "memory");
;         __hip_atomic_fetch_add(ctr, 1u, __ATOMIC_RELAXED, __HIP_MEMORY_SCOPE_AGENT);
;         unsigned spins = 0;
;         while (__hip_atomic_load(ctr, __ATOMIC_RELAXED, __HIP_MEMORY_SCOPE_AGENT) < target) { __builtin_amdgcn_s_sleep(2); if (++spins > (1u << 24)) break; }
;         __builtin_amdgcn_fence(__ATOMIC_ACQUIRE, "agent");
;         asm volatile("s_waitcnt vmcnt(0)" ::: "memory");
;     }
;     __syncthreads();
; }
; __global__ void __launch_bounds__(512, 2) mk_fwd(Args a) {
;     ...
;     GSYNC();
.Lmy_gb1_rel:
	buffer_inv sc1
	s_waitcnt vmcnt(0)
	s_add_i32 s7, s6, 0x17000
	v_mov_b32_e32 v0, s7
	v_mov_b32_e32 v1, 1
	global_atomic_add v0, v1, s[22:23]
	s_waitcnt vmcnt(0)
	s_branch .Lmy_gb1_done
.Lmy_gb1_follow:
	buffer_inv sc1
	s_add_i32 s7, s6, 0x17000
	v_mov_b32_e32 v0, s7
	s_mov_b32 s8, 0x400000

; #define LAS __attribute__((address_space(3)))
; __global__ void __launch_bounds__(512, 2) mk_fwd(Args a) {
;     ...
;     { LAS int* vslot = (LAS int*)(lds + RING_BYTES);
;       if (threadIdx.x == 0) { const unsigned my_rank = *(LAS unsigned*)(lds + RING_BYTES + 64); bool ok = (G % 8 == 0) && (my_xcc < 8u);
;           for (int j = 0; j < 8; ++j) ok = ok && (__hip_atomic_load(bar_ctr + 512 + 64 * j, __ATOMIC_RELAXED, __HIP_MEMORY_SCOPE_AGENT) == (unsigned)(G / 8));
;           *vslot = ok ? (int)(my_rank * 8u + my_xcc) : bx; }
;       __syncthreads(); vbx = __builtin_amdgcn_readfirstlane(*vslot); }
.Lmy_gb1_acq:
.Lmy_gb1_done:
.LBB0_82:
	s_or_b64 exec, exec, s[4:5]
	s_barrier
	s_mov_b64 s[4:5], exec
	v_readlane_b32 s0, v255, 0
	v_readlane_b32 s1, v255, 1
	s_and_b64 s[0:1], s[4:5], s[0:1]
	s_mov_b64 exec, s[0:1]
	s_cbranch_execz .LBB0_93
	s_add_i32 s1, 0, 0x20040
	s_and_b32 s0, s3, 15
	v_mov_b32_e32 v0, s1
	s_and_b32 s1, s24, 7
	ds_read_b32 v0, v0
	s_cmp_eq_u32 s1, 0
	s_cselect_b64 s[6:7], -1, 0
	s_cmp_lt_u32 s0, 8
	s_cselect_b64 s[8:9], -1, 0
	s_and_b64 s[6:7], s[6:7], s[8:9]
	s_andn2_b64 vcc, exec, s[6:7]
	s_mov_b64 s[6:7], 0
	s_cbranch_vccnz .LBB0_92
	v_mov_b32_e32 v1, 0
	global_load_dword v2, v1, s[22:23] offset:2048 sc1
	s_ashr_i32 s1, s24, 31
	s_lshr_b32 s1, s1, 29
	s_add_i32 s1, s24, s1
	s_ashr_i32 s1, s1, 3
	s_waitcnt vmcnt(0)
	v_cmp_ne_u32_e32 vcc, s1, v2
	s_cbranch_vccnz .LBB0_92
	global_load_dword v1, v1, s[22:23] offset:2304 sc1
	s_waitcnt vmcnt(0)
	v_cmp_ne_u32_e32 vcc, s1, v1
	s_cbranch_vccnz .LBB0_92
	v_mov_b32_e32 v1, 0
	global_load_dword v2, v1, s[22:23] offset:2560 sc1
	s_waitcnt vmcnt(0)
	v_cmp_ne_u32_e32 vcc, s1, v2
	s_cbranch_vccnz .LBB0_92
	global_load_dword v1, v1, s[22:23] offset:2816 sc1
	s_waitcnt vmcnt(0)
	v_cmp_ne_u32_e32 vcc, s1, v1
	s_cbranch_vccnz .LBB0_92
	v_mov_b32_e32 v1, 0
	global_load_dword v2, v1, s[22:23] offset:3072 sc1
	s_waitcnt vmcnt(0)
	v_cmp_ne_u32_e32 vcc, s1, v2
	s_cbranch_vccnz .LBB0_92
	global_load_dword v1, v1, s[22:23] offset:3328 sc1
	s_waitcnt vmcnt(0)
	v_cmp_ne_u32_e32 vcc, s1, v1
	s_cbranch_vccnz .LBB0_92
	v_mov_b32_e32 v1, 0
	global_load_dword v2, v1, s[22:23] offset:3584 sc1
	s_waitcnt vmcnt(0)
	v_cmp_ne_u32_e32 vcc, s1, v2
	s_cbranch_vccnz .LBB0_92
	global_load_dword v1, v1, s[22:23] offset:3840 sc1
	s_waitcnt vmcnt(0)
	v_cmp_eq_u32_e64 s[6:7], s1, v1

; #define LAS __attribute__((address_space(3)))
;     int tid_l = threadIdx.x; asm volatile("" : "+v"(tid_l));
;     const int tid = tid_l, lane = tid & 63, wave = __builtin_amdgcn_readfirstlane(tid >> 6), qi = lane & 15, g = lane >> 4;
;     LAS unsigned char* ldsK = lds + L_K; LAS unsigned char* ldsV = lds + L_V; LAS float* tbl = (LAS float*)(lds + L_T); LAS float* pmt = (LAS float*)(lds + L_PM);
;     const int G = gridDim.x, bx = blockIdx.x;
;     const int na0 = (int)((long)bx * NITEM_A / G), nA = (int)((long)(bx + 1) * NITEM_A / G) - na0;
;     const int nb0 = (int)((long)bx * NITEM_B / G), nB = (int)((long)(bx + 1) * NITEM_B / G) - nb0;
.Lmy_gb2_acq:
.Lmy_gb2_done:
.LBB0_134:
	s_or_b64 exec, exec, s[4:5]
	v_and_b32_e32 v242, 7, v254
	v_lshlrev_b32_e32 v242, 2, v242
	global_load_dword v241, v242, s[10:11]
	s_waitcnt vmcnt(0)
	s_mul_hi_i32 s5, s2, 0x500
	s_mul_i32 s4, s2, 0x500
	s_or_b64 s[0:1], s[4:5], s[24:25]
	v_mov_b32_e32 v147, v254
	s_mov_b32 s0, 0
	s_barrier
	s_cmp_lg_u64 s[0:1], 0
	v_readfirstlane_b32 s48, v147
	s_cbranch_scc0 .LBB0_149
	s_ashr_i32 s8, s25, 31
	s_add_u32 s0, s24, s8
	s_mov_b32 s9, s8
	s_addc_u32 s1, s25, s8
	s_xor_b64 s[12:13], s[0:1], s[8:9]
	v_cvt_f32_u32_e32 v0, s12
	v_cvt_f32_u32_e32 v1, s13
	s_sub_u32 s3, 0, s12
	s_subb_u32 s14, 0, s13
	v_fmamk_f32 v0, v1, 0x4f800000, v0
	v_rcp_f32_e32 v0, v0
	s_nop 0
	v_mul_f32_e32 v0, 0x5f7ffffc, v0
	v_mul_f32_e32 v1, 0x2f800000, v0
	v_trunc_f32_e32 v1, v1
	v_fmamk_f32 v0, v1, 0xcf800000, v0
	v_cvt_u32_f32_e32 v1, v1
	v_cvt_u32_f32_e32 v0, v0
	v_readfirstlane_b32 s15, v1
	v_readfirstlane_b32 s0, v0
	s_mul_i32 s1, s3, s15
	s_mul_hi_u32 s45, s3, s0
	s_mul_i32 s44, s14, s0
	s_add_i32 s1, s45, s1
	s_add_i32 s1, s1, s44
	s_mul_i32 s46, s3, s0
	s_mul_i32 s45, s0, s1
	s_mul_hi_u32 s47, s0, s46
	s_mul_hi_u32 s44, s0, s1
	s_add_u32 s45, s47, s45
	s_addc_u32 s44, 0, s44
	s_mul_hi_u32 s49, s15, s46
	s_mul_i32 s46, s15, s46
	s_add_u32 s45, s45, s46
	s_mul_hi_u32 s47, s15, s1
	s_addc_u32 s44, s44, s49
	s_addc_u32 s45, s47, 0
	s_mul_i32 s1, s15, s1
	s_add_u32 s1, s44, s1
	s_addc_u32 s44, 0, s45
	s_add_u32 s45, s0, s1
	s_cselect_b64 s[0:1], -1, 0
	s_cmp_lg_u64 s[0:1], 0
	s_addc_u32 s15, s15, s44
	s_mul_i32 s0, s3, s15
	s_mul_hi_u32 s1, s3, s45
	s_add_i32 s0, s1, s0
	s_mul_i32 s14, s14, s45
	s_add_i32 s0, s0, s14
	s_mul_i32 s3, s3, s45
	s_mul_hi_u32 s14, s15, s3
	s_mul_i32 s44, s15, s3
	s_mul_i32 s47, s45, s0
	s_mul_hi_u32 s3, s45, s3
	s_mul_hi_u32 s46, s45, s0
	s_add_u32 s3, s3, s47
	s_addc_u32 s46, 0, s46
	s_add_u32 s3, s3, s44
	s_mul_hi_u32 s1, s15, s0
	s_addc_u32 s3, s46, s14
	s_addc_u32 s1, s1, 0
	s_mul_i32 s0, s15, s0
	s_add_u32 s0, s3, s0
	s_addc_u32 s3, 0, s1
	s_add_u32 s44, s45, s0
	s_cselect_b64 s[0:1], -1, 0
	s_cmp_lg_u64 s[0:1], 0
	s_addc_u32 s3, s15, s3
	s_ashr_i32 s0, s5, 31
	s_add_u32 s14, s4, s0
	s_mov_b32 s1, s0
	s_addc_u32 s15, s5, s0
	s_xor_b64 s[14:15], s[14:15], s[0:1]
	s_mul_i32 s45, s14, s3
	s_mul_hi_u32 s46, s14, s44
	s_mul_hi_u32 s5, s14, s3
	s_add_u32 s45, s46, s45
	s_addc_u32 s5, 0, s5
	s_mul_hi_u32 s47, s15, s44
	s_mul_i32 s44, s15, s44
	s_add_u32 s44, s45, s44
	s_mul_hi_u32 s46, s15, s3
	s_addc_u32 s5, s5, s47
	s_addc_u32 s44, s46, 0
	s_mul_i32 s3, s15, s3
	s_add_u32 s3, s5, s3
	s_addc_u32 s5, 0, s44
	s_mul_i32 s44, s12, s5
	s_mul_hi_u32 s45, s12, s3
	s_add_i32 s44, s45, s44
	s_mul_i32 s45, s13, s3
	s_add_i32 s49, s44, s45
	s_sub_i32 s46, s15, s49
	s_mul_i32 s44, s12, s3
	s_sub_u32 s14, s14, s44
	s_cselect_b64 s[44:45], -1, 0
	s_cmp_lg_u64 s[44:45], 0
	s_subb_u32 s50, s46, s13
	s_sub_u32 s51, s14, s12
	s_cselect_b64 s[46:47], -1, 0
	s_cmp_lg_u64 s[46:47], 0
	s_subb_u32 s46, s50, 0
	s_cmp_ge_u32 s46, s13
	s_cselect_b32 s47, -1, 0
	s_cmp_ge_u32 s51, s12
	s_cselect_b32 s50, -1, 0
	s_cmp_eq_u32 s46, s13
	s_cselect_b32 s46, s50, s47
	s_add_u32 s47, s3, 1
	s_addc_u32 s50, s5, 0
	s_add_u32 s51, s3, 2
	s_addc_u32 s54, s5, 0
	s_cmp_lg_u32 s46, 0
	s_cselect_b32 s46, s51, s47
	s_cselect_b32 s47, s54, s50
	s_cmp_lg_u64 s[44:45], 0
	s_subb_u32 s15, s15, s49
	s_cmp_ge_u32 s15, s13
	s_cselect_b32 s44, -1, 0
	s_cmp_ge_u32 s14, s12
	s_cselect_b32 s12, -1, 0
	s_cmp_eq_u32 s15, s13
	s_cselect_b32 s12, s12, s44
	s_cmp_lg_u32 s12, 0
	s_cselect_b32 s13, s47, s5
	s_cselect_b32 s12, s46, s3
	s_xor_b64 s[0:1], s[0:1], s[8:9]
	s_xor_b64 s[8:9], s[12:13], s[0:1]
	s_sub_u32 s12, s8, s0
	v_cvt_f32_u32_e32 v0, s24
	s_cbranch_execnz .LBB0_137

; __global__ void __launch_bounds__(512, 2) mk_fwd(Args a) {
;     ...
;     for (int repb = 0; repb < REP_P2B; ++repb)
;     for (unsigned idx = (unsigned)bx * 512u + (unsigned)threadIdx.x; idx < (unsigned)TT * 32u; idx += (unsigned)G * 512u) {
;         const size_t tok = idx >> 5; const int part = (int)(idx & 31u), hh = part >> 3;
;         const float l0 = LSE[tok * 4 + hh], l1 = LSE[((size_t)TT + tok) * 4 + hh], l2 = LSE[((size_t)2 * TT + tok) * 4 + hh];
;         const float mx = fmaxf(l0, fmaxf(l1, l2)); float w0 = __builtin_amdgcn_exp2f(l0 - mx), w1 = __builtin_amdgcn_exp2f(l1 - mx), w2 = __builtin_amdgcn_exp2f(l2 - mx);
;         const float inv = 1.f / (w0 + w1 + w2); w0 *= inv; w1 *= inv; w2 *= inv;
.Lmy_gb3_acq:
.Lmy_gb3_done:
.LBB0_272:
	s_or_b64 exec, exec, s[4:5]
	v_lshl_add_u32 v8, s2, 9, v254
	s_mov_b32 s0, 0x280000
	v_cmp_gt_u32_e32 vcc, s0, v8
	s_barrier
	s_and_saveexec_b64 s[2:3], vcc
	s_cbranch_execz .LBB0_275
	v_lshrrev_b32_e32 v0, 1, v254
	v_and_b32_e32 v4, 31, v254
	v_and_b32_e32 v0, 12, v0
	v_mov_b32_e32 v1, 0
	v_lshl_add_u64 v[2:3], s[14:15], 0, v[0:1]
	v_lshlrev_b32_e32 v0, 3, v4
	v_lshlrev_b32_e32 v4, 4, v4
	v_mov_b32_e32 v5, v1
	s_lshl_b32 s7, s24, 9
	v_lshl_add_u64 v[4:5], s[20:21], 0, v[4:5]
	v_lshl_add_u64 v[6:7], s[16:17], 0, v[0:1]
	s_mov_b64 s[4:5], 0
	s_mov_b32 s6, 0x41000000
	s_movk_i32 s8, 0x300
	s_mov_b32 s9, 0x27ffff

; #define GSYNC() do { ++bar_n; grid_barrier(bar_ctr, bar_n * (unsigned)G); } while (0)
; __device__ __forceinline__ void grid_barrier(unsigned* ctr, unsigned target) {
;     asm volatile("s_waitcnt vmcnt(0)" ::: "memory");
;     __syncthreads();
;     if (threadIdx.x == 0) {
;         __builtin_amdgcn_fence(__ATOMIC_RELEASE, "agent");
;         asm volatile("s_waitcnt vmcnt(0)" ::: "memory");
;         __hip_atomic_fetch_add(ctr, 1u, __ATOMIC_RELAXED, __HIP_MEMORY_SCOPE_AGENT);
;         unsigned spins = 0;
;         while (__hip_atomic_load(ctr, __ATOMIC_RELAXED, __HIP_MEMORY_SCOPE_AGENT) < target) { __builtin_amdgcn_s_sleep(2); if (++spins > (1u << 24)) break; }
;         __builtin_amdgcn_fence(__ATOMIC_ACQUIRE, "agent");
;         asm volatile("s_waitcnt vmcnt(0)" ::: "memory");
;     }
;     __syncthreads();
; }
; __global__ void __launch_bounds__(512, 2) mk_fwd(Args a) {
;     ...
;     GSYNC();
.Lmy_gb4_rel:
	buffer_inv sc1
	s_waitcnt vmcnt(0)
	s_add_i32 s5, s4, 0x17000
	v_mov_b32_e32 v0, s5
	v_mov_b32_e32 v1, 1
	global_atomic_add v0, v1, s[22:23]
	s_waitcnt vmcnt(0)
	s_branch .Lmy_gb4_done
.Lmy_gb4_follow:
	buffer_inv sc1
	s_add_i32 s5, s4, 0x17000
	v_mov_b32_e32 v0, s5
	s_mov_b32 s6, 0x400000

; #define PG8_WAIT_V(n) asm volatile("s_waitcnt vmcnt(" #n ")" ::: "memory")
; #define PG8_BAR __builtin_amdgcn_s_barrier()
; template <class Epi, class Sched, bool ALIGN_EPI = false, bool SP2 = false, bool FP8 = false>
; __device__ __forceinline__ void gemm_phase(PG8_LAS unsigned char* lds, const Gemm g, const Sched& S, const Epi& E) {
;     ...
;     const int tid = tid_l, wid = __builtin_amdgcn_readfirstlane(tid >> 6), lane = tid & 63, wr = wid >> 2, wc = wid & 3, fr = lane & 15, fq = lane >> 4;
;     const int K = g.K, nt = K / BK;
;     unsigned voffA[2], voffB[2];
; #pragma unroll
;     for (int i = 0; i < 2; ++i) { int R, C; stage_rc(tid * 16 + i * 8192, R, C); const int Rb = Epi::PERM ? ((R & ~31) + perm32(R & 31)) : R;
;         voffA[i] = (unsigned)(R * K + C) * 2u; voffB[i] = (unsigned)(Rb * K + C) * 2u; }
;     const size_t kstep = (size_t)(BK * 2);
;     const size_t hstep = (size_t)HALF * K * 2;
;     const size_t tstep = 2 * hstep;
;     const unsigned ldsw = (unsigned)wid * 1024u;
;     const int aoff = lds_byte(wr * 64 + fr, fq * 8), boff = lds_byte(wc * 32 + fr, fq * 8);
;     ...
;     Unit cur, nxt; int ui = 0;
;     if (!S.next(0, cur)) return;
;     f32x4 acc[2][2][4][2];
; #pragma unroll
;     for (int a = 0; a < 2; ++a)
; #pragma unroll
;         for (int b = 0; b < 2; ++b)
; #pragma unroll
;             for (int m = 0; m < 4; ++m)
; #pragma unroll
;                 for (int n = 0; n < 2; ++n) { acc[a][b][m][n] = (f32x4){0.f, 0.f, 0.f, 0.f}; if constexpr (FP8) asm volatile("" : "+v"(acc[a][b][m][n])); }
;     bf16x8 At[4][2], B0[2][2], B1[2][2];
;     typedef int v4i_t __attribute__((ext_vector_type(4))); typedef int v8i_t __attribute__((ext_vector_type(8)));
;     const char* cA = (const char*)g.A + (size_t)cur.pm * tstep; const char* cB = (const char*)g.Bt + (size_t)cur.pn * tstep;
;     S.a_ready(cur);
;     if constexpr (SP2) {
;         PG8_STAGE(PG8_SB(0, 0), cB, voffB); PG8_STAGE(PG8_SB(0, 1), cB + hstep, voffB); PG8_STAGE(PG8_SA(0, 0), cA, voffA); PG8_STAGE(PG8_SA(0, 1), cA + hstep, voffA);
;         if (wr == 1) PG8_BAR;
;         PG8_WAIT_V(2); PG8_BAR;
; __global__ void __launch_bounds__(512, 2) mk_fwd(Args a) {
;     ...
;     { pg8::Gemm g{OA, Wa_t, TT, DM, 768 / 2}; pg8::StaticOrder S; S.init(TT, DM, G, vbx); pg8::EpiGate2 E{MRG, (const unsigned char*)Gt};
;       pg8::gemm_phase<pg8::EpiGate2, pg8::StaticOrder, true, true, true>(lds, g, S, E); }
.Lmy_gb4_acq:
.Lmy_gb4_done:
.LBB0_292:
	s_or_b64 exec, exec, s[2:3]
	v_mov_b32_e32 v130, v254
	s_cmpk_lt_i32 s33, 0x500
	s_barrier
	s_cselect_b64 s[6:7], -1, 0
	s_cmpk_gt_i32 s33, 0x4ff
	v_readfirstlane_b32 s2, v130
	s_cbranch_scc1 .LBB0_314
	v_bfe_i32 v2, v130, 27, 1
	v_lshlrev_b32_e32 v0, 4, v130
	v_lshrrev_b32_e32 v2, 22, v2
	v_add_u32_e32 v2, v0, v2
	v_and_b32_e32 v2, 0xfffffc00, v2
	v_sub_u32_e32 v2, v0, v2
	v_lshrrev_b32_e32 v3, 4, v2
	v_ashrrev_i32_e32 v1, 31, v130
	v_bitop3_b32 v2, v3, v2, 32 bitop3:0x6c
	v_lshrrev_b32_e32 v1, 26, v1
	v_ashrrev_i32_e32 v4, 31, v2
	v_add_u32_e32 v1, v130, v1
	v_lshrrev_b32_e32 v4, 26, v4
	v_ashrrev_i32_e32 v1, 6, v1
	v_add_u32_e32 v4, v2, v4
	v_lshlrev_b32_e32 v3, 3, v1
	v_ashrrev_i32_e32 v5, 6, v4
	v_and_b32_e32 v4, 0xc0, v4
	v_and_b32_e32 v3, -16, v3
	v_lshlrev_b32_e32 v1, 5, v1
	v_sub_u32_e32 v2, v2, v4
	v_mov_b32_e32 v4, 1
	v_add_u32_e32 v3, v5, v3
	v_and_b32_e32 v1, 32, v1
	v_ashrrev_i16_sdwa v2, v4, sext(v2) dst_sel:DWORD dst_unused:UNUSED_PAD src0_sel:DWORD src1_sel:BYTE_0
	v_add_u32_sdwa v1, v1, sext(v2) dst_sel:DWORD dst_unused:UNUSED_PAD src0_sel:DWORD src1_sel:WORD_0
	v_lshlrev_b32_e32 v2, 1, v3
	v_lshrrev_b32_e32 v6, 2, v3
	v_and_b32_e32 v5, 3, v5
	s_mov_b32 s0, 0x1ffffe0
	v_and_b32_e32 v2, 24, v2
	v_and_b32_e32 v6, 4, v6
	v_and_or_b32 v5, v3, s0, v5
	v_or3_b32 v2, v5, v6, v2
	s_movk_i32 s1, 0x180
	v_mul_lo_u32 v3, v3, s1
	v_mul_lo_u32 v2, v2, s1
	v_add_u32_e32 v0, 0x2000, v0
	v_add_lshl_u32 v146, v1, v3, 1
	v_add_lshl_u32 v147, v2, v1, 1
	v_ashrrev_i32_e32 v1, 31, v0
	v_lshrrev_b32_e32 v1, 22, v1
	v_add_u32_e32 v1, v0, v1
	v_ashrrev_i32_e32 v1, 10, v1
	v_mul_i32_i24_e32 v2, 0x400, v1
	v_sub_u32_e32 v0, v0, v2
	v_lshrrev_b32_e32 v2, 4, v0
	v_bitop3_b32 v0, v2, v0, 32 bitop3:0x6c
	v_ashrrev_i32_e32 v3, 31, v0
	v_lshrrev_b32_e32 v3, 26, v3
	v_add_u32_e32 v3, v0, v3
	v_lshlrev_b32_e32 v2, 3, v1
	v_ashrrev_i32_e32 v5, 6, v3
	v_and_b32_e32 v3, 0xc0, v3
	v_and_b32_e32 v2, -16, v2
	v_lshlrev_b32_e32 v1, 5, v1
	v_sub_u32_e32 v0, v0, v3
	v_add_u32_e32 v2, v5, v2
	v_and_b32_e32 v1, 32, v1
	v_ashrrev_i16_sdwa v0, v4, sext(v0) dst_sel:DWORD dst_unused:UNUSED_PAD src0_sel:DWORD src1_sel:BYTE_0
	v_add_u32_sdwa v0, v1, sext(v0) dst_sel:DWORD dst_unused:UNUSED_PAD src0_sel:DWORD src1_sel:WORD_0
	v_lshlrev_b32_e32 v1, 1, v2
	v_lshrrev_b32_e32 v3, 2, v2
	v_and_b32_e32 v4, 3, v5
	v_and_b32_e32 v1, 24, v1
	v_and_b32_e32 v3, 4, v3
	v_and_or_b32 v4, v2, s0, v4
	s_lshr_b32 s0, s76, 29
	v_or3_b32 v1, v4, v3, v1
	s_add_i32 s0, s33, s0
	v_mul_lo_u32 v2, v2, s1
	v_mul_lo_u32 v1, v1, s1
	s_ashr_i32 s5, s2, 6
	s_ashr_i32 s1, s0, 3
	s_and_b32 s0, s0, -8
	s_ashr_i32 s3, s2, 8
	s_lshl_b32 s66, s5, 10
	s_sub_i32 s0, s33, s0
	s_cmp_lt_i32 s0, 0
	s_movk_i32 s67, 0xa1
	s_cselect_b32 s4, s67, 0xa0
	s_mul_i32 s0, s0, s4
	s_add_i32 s0, s0, s1
	s_ashr_i32 s1, s0, 31
	s_lshr_b32 s1, s1, 27
	s_add_i32 s1, s0, s1
	s_ashr_i32 s4, s1, 5
	s_and_b32 s1, s1, 0xffe0
	s_sub_i32 s0, s0, s1
	s_bfe_i32 s1, s0, 0x80000
	s_bfe_u32 s1, s1, 0x3000c
	s_add_i32 s1, s0, s1
	s_lshl_b32 s9, s4, 3
	s_bfe_i32 s4, s1, 0x80000
	s_and_b32 s1, s1, 0xf8
	s_sub_i32 s0, s0, s1
	s_sext_i32_i16 s12, s4
	s_sext_i32_i8 s0, s0
	s_mov_b32 s8, 0
	s_add_i32 s64, s9, s0
	s_ashr_i32 s0, s12, 3
	s_lshr_b32 s4, s12, 3
	s_mov_b32 s9, s8
	s_mov_b32 s10, s8
	s_mov_b32 s11, s8
	s_mul_hi_i32 s1, s0, 0x30000
	s_mul_i32 s0, s0, 0x30000
	v_readlane_b32 s12, v255, 2
	v_add_lshl_u32 v148, v0, v2, 1
	v_add_lshl_u32 v149, v1, v0, 1
	v_mov_b64_e32 v[0:1], s[8:9]
	v_mov_b64_e32 v[114:115], s[10:11]
	v_mov_b64_e32 v[118:119], s[10:11]
	s_waitcnt vmcnt(0)
	v_mov_b64_e32 v[98:99], s[10:11]
	v_mov_b64_e32 v[102:103], s[10:11]
	v_mov_b64_e32 v[82:83], s[10:11]
	v_mov_b64_e32 v[86:87], s[10:11]
	v_mov_b64_e32 v[66:67], s[10:11]
	v_mov_b64_e32 v[70:71], s[10:11]
	v_mov_b64_e32 v[122:123], s[10:11]
	v_mov_b64_e32 v[126:127], s[10:11]
	v_mov_b64_e32 v[106:107], s[10:11]
	v_mov_b64_e32 v[110:111], s[10:11]
	v_mov_b64_e32 v[90:91], s[10:11]
	v_mov_b64_e32 v[94:95], s[10:11]
	v_mov_b64_e32 v[74:75], s[10:11]
	v_mov_b64_e32 v[78:79], s[10:11]
	v_mov_b64_e32 v[50:51], s[10:11]
	v_mov_b64_e32 v[54:55], s[10:11]
	v_mov_b64_e32 v[34:35], s[10:11]
	v_mov_b64_e32 v[38:39], s[10:11]
	v_mov_b64_e32 v[18:19], s[10:11]
	v_mov_b64_e32 v[22:23], s[10:11]
	v_mov_b64_e32 v[4:5], s[8:9]
	v_mov_b64_e32 v[8:9], s[8:9]
	v_mov_b64_e32 v[58:59], s[10:11]
	v_mov_b64_e32 v[62:63], s[10:11]
	v_mov_b64_e32 v[42:43], s[10:11]
	v_mov_b64_e32 v[46:47], s[10:11]
	v_mov_b64_e32 v[26:27], s[10:11]
	v_mov_b64_e32 v[30:31], s[10:11]
	v_mov_b64_e32 v[14:15], s[10:11]
	v_readlane_b32 s13, v255, 3
	s_add_u32 s62, s12, s0
	v_mov_b64_e32 v[2:3], s[10:11]
	v_mov_b64_e32 v[112:113], s[8:9]
	v_mov_b64_e32 v[116:117], s[8:9]
	v_mov_b64_e32 v[96:97], s[8:9]
	v_mov_b64_e32 v[100:101], s[8:9]
	v_mov_b64_e32 v[80:81], s[8:9]
	v_mov_b64_e32 v[84:85], s[8:9]
	v_mov_b64_e32 v[64:65], s[8:9]
	v_mov_b64_e32 v[68:69], s[8:9]
	v_mov_b64_e32 v[120:121], s[8:9]
	v_mov_b64_e32 v[124:125], s[8:9]
	v_mov_b64_e32 v[104:105], s[8:9]
	v_mov_b64_e32 v[108:109], s[8:9]
	v_mov_b64_e32 v[88:89], s[8:9]
	v_mov_b64_e32 v[92:93], s[8:9]
	v_mov_b64_e32 v[72:73], s[8:9]
	v_mov_b64_e32 v[76:77], s[8:9]
	v_mov_b64_e32 v[48:49], s[8:9]
	v_mov_b64_e32 v[52:53], s[8:9]
	v_mov_b64_e32 v[32:33], s[8:9]
	v_mov_b64_e32 v[36:37], s[8:9]
	v_mov_b64_e32 v[16:17], s[8:9]
	v_mov_b64_e32 v[20:21], s[8:9]
	v_mov_b64_e32 v[6:7], s[10:11]
	v_mov_b64_e32 v[10:11], s[10:11]
	v_mov_b64_e32 v[56:57], s[8:9]
	v_mov_b64_e32 v[60:61], s[8:9]
	v_mov_b64_e32 v[40:41], s[8:9]
	v_mov_b64_e32 v[44:45], s[8:9]
	v_mov_b64_e32 v[24:25], s[8:9]
	v_mov_b64_e32 v[28:29], s[8:9]
	v_mov_b64_e32 v[12:13], s[8:9]
	s_addc_u32 s63, s13, s1
	s_add_i32 s68, s66, 0
	v_mov_b32_e32 v128, v147
	s_add_i32 m0, s68, 0x10000
	s_mul_i32 s10, s64, 0x30000
	global_load_lds_dwordx4 v128, s[62:63]
	v_mov_b32_e32 v128, v149
	s_add_i32 m0, s68, 0x12000
	s_add_u32 s0, s62, 0x18000
	global_load_lds_dwordx4 v128, s[62:63]
	v_mov_b32_e32 v128, v147
	s_addc_u32 s1, s63, 0
	s_add_i32 m0, s68, 0x14000
	s_mul_hi_i32 s9, s64, 0x30000
	global_load_lds_dwordx4 v128, s[0:1]
	v_mov_b32_e32 v128, v149
	s_add_i32 m0, s68, 0x16000
	s_add_u32 s10, s16, s10
	global_load_lds_dwordx4 v128, s[0:1]
	v_mov_b32_e32 v128, v146
	s_addc_u32 s11, s17, s9
	s_mov_b32 m0, s68
	s_add_i32 s69, s68, 0x2000
	global_load_lds_dwordx4 v128, s[10:11]
	v_mov_b32_e32 v128, v148
	s_mov_b32 m0, s69
	s_add_u32 s0, s10, 0x18000
	global_load_lds_dwordx4 v128, s[10:11]
	s_addc_u32 s1, s11, 0
	s_add_i32 s70, s68, 0x4000
	v_mov_b32_e32 v128, v146
	s_mov_b32 m0, s70
	s_add_i32 s71, s68, 0x6000
	global_load_lds_dwordx4 v128, s[0:1]
	v_mov_b32_e32 v128, v148
	s_mov_b32 m0, s71
	s_cmp_eq_u32 s3, 1
	global_load_lds_dwordx4 v128, s[0:1]
	s_mov_b32 s72, 0x10000
	s_cselect_b64 s[12:13], -1, 0
	s_cmp_lg_u32 s3, 1
	s_mov_b64 s[14:15], 0x18000
	s_cbranch_scc1 .LBB0_295
	s_barrier

; __device__ __forceinline__ void grid_barrier(unsigned* ctr, unsigned target) {
;     ...
;         while (__hip_atomic_load(ctr, __ATOMIC_RELAXED, __HIP_MEMORY_SCOPE_AGENT) < target) { __builtin_amdgcn_s_sleep(2); if (++spins > (1u << 24)) break; }
.Lmy_gb5_follow:
	buffer_inv sc1
	s_add_i32 s5, s4, 0x17000
	v_mov_b32_e32 v0, s5
	s_mov_b32 s8, 0x400000

;     __host__ __device__ bool next(int i, Unit& u) const {
;         const long L = (long)i * G + c; if (L >= nwg) return false;
;         int wgid = (int)L; { const int q = nwg / NXCD, r = nwg % NXCD, xcd = wgid % NXCD, off = wgid / NXCD; wgid = (xcd < r ? xcd * (q + 1) : r * (q + 1) + (xcd - r) * q) + off; }
;         const int nig = WGM * nN, gid = wgid / nig, fm = gid * WGM, gsz = (nM - fm) < WGM ? (nM - fm) : WGM;
;         u.pm = fm + ((wgid % nig) % gsz); u.pn = (wgid % nig) / gsz; return true;
; __global__ void __launch_bounds__(512, 2) mk_fwd(Args a) {
;     ...
;     for (int rep = 0; rep < REP_P4; ++rep) { pg8::Gemm g{MRG, Wout_t, TT, DM, DM / 2}; pg8::StaticOrder S; S.init(TT, DM, G, vbx); pg8::EpiRes<true> E{x_p, x_s, out, X1B, SSQ1, 1.f / 512.f};
.Lmy_gb5_acq:
.Lmy_gb5_done:
.LBB0_331:
	s_or_b64 exec, exec, s[2:3]
	v_mov_b32_e32 v128, v254
	s_barrier
	s_and_b64 vcc, exec, s[6:7]
	v_readfirstlane_b32 s4, v128
	s_cbranch_vccz .LBB0_333
	s_lshr_b32 s0, s76, 29
	s_add_i32 s0, s33, s0
	s_ashr_i32 s1, s0, 3
	s_and_b32 s0, s0, -8
	s_sub_i32 s0, s33, s0
	s_cmp_lt_i32 s0, 0
	s_movk_i32 s2, 0xa1
	s_cselect_b32 s2, s2, 0xa0
	s_mul_i32 s0, s0, s2
	s_add_i32 s0, s0, s1
	s_ashr_i32 s1, s0, 31
	s_lshr_b32 s1, s1, 27
	s_add_i32 s1, s0, s1
	s_ashr_i32 s2, s1, 5
	s_and_b32 s1, s1, 0xffe0
	s_sub_i32 s0, s0, s1
	s_bfe_i32 s1, s0, 0x80000
	s_bfe_u32 s1, s1, 0x3000c
	s_add_i32 s1, s0, s1
	s_bfe_i32 s3, s1, 0x80000
	s_and_b32 s1, s1, 0xf8
	s_sub_i32 s0, s0, s1
	s_lshl_b32 s2, s2, 3
	s_sext_i32_i16 s3, s3
	s_sext_i32_i8 s0, s0
	s_add_i32 s52, s2, s0
	s_ashr_i32 s50, s3, 3

; #define PG8_WAIT_V(n) asm volatile("s_waitcnt vmcnt(" #n ")" ::: "memory")
; template <class Epi, class Sched, bool ALIGN_EPI = false, bool SP2 = false, bool FP8 = false>
; __device__ __forceinline__ void gemm_phase(PG8_LAS unsigned char* lds, const Gemm g, const Sched& S, const Epi& E) {
;     ...
;     const int tid = tid_l, wid = __builtin_amdgcn_readfirstlane(tid >> 6), lane = tid & 63, wr = wid >> 2, wc = wid & 3, fr = lane & 15, fq = lane >> 4;
;     const int K = g.K, nt = K / BK;
;     unsigned voffA[2], voffB[2];
; #pragma unroll
;     for (int i = 0; i < 2; ++i) { int R, C; stage_rc(tid * 16 + i * 8192, R, C); const int Rb = Epi::PERM ? ((R & ~31) + perm32(R & 31)) : R;
;         voffA[i] = (unsigned)(R * K + C) * 2u; voffB[i] = (unsigned)(Rb * K + C) * 2u; }
;     const size_t kstep = (size_t)(BK * 2);
;     const size_t hstep = (size_t)HALF * K * 2;
;     const size_t tstep = 2 * hstep;
;     const unsigned ldsw = (unsigned)wid * 1024u;
;     const int aoff = lds_byte(wr * 64 + fr, fq * 8), boff = lds_byte(wc * 32 + fr, fq * 8);
;     ...
;     Unit cur, nxt; int ui = 0;
;     if (!S.next(0, cur)) return;
;     f32x4 acc[2][2][4][2];
; #pragma unroll
;     for (int a = 0; a < 2; ++a)
; #pragma unroll
;         for (int b = 0; b < 2; ++b)
; #pragma unroll
;             for (int m = 0; m < 4; ++m)
; #pragma unroll
;                 for (int n = 0; n < 2; ++n) { acc[a][b][m][n] = (f32x4){0.f, 0.f, 0.f, 0.f}; if constexpr (FP8) asm volatile("" : "+v"(acc[a][b][m][n])); }
;     bf16x8 At[4][2], B0[2][2], B1[2][2];
;     typedef int v4i_t __attribute__((ext_vector_type(4))); typedef int v8i_t __attribute__((ext_vector_type(8)));
;     const char* cA = (const char*)g.A + (size_t)cur.pm * tstep; const char* cB = (const char*)g.Bt + (size_t)cur.pn * tstep;
;     S.a_ready(cur);
;     if constexpr (SP2) {
;         PG8_STAGE(PG8_SB(0, 0), cB, voffB); PG8_STAGE(PG8_SB(0, 1), cB + hstep, voffB); PG8_STAGE(PG8_SA(0, 0), cA, voffA); PG8_STAGE(PG8_SA(0, 1), cA + hstep, voffA);
;         if (wr == 1) PG8_BAR;
;         PG8_WAIT_V(2); PG8_BAR;
; __global__ void __launch_bounds__(512, 2) mk_fwd(Args a) {
;     ...
;     for (int rep = 0; rep < REP_P5; ++rep) { pg8::Gemm g{X1B, Wup_t, TT, DFF, DM}; pg8::StaticOrder S; S.init(TT, DFF, G, vbx); pg8::EpiUp E{Hb, SSQ1};
;       pg8::gemm_phase<pg8::EpiUp, pg8::StaticOrder, true, true>(lds, g, S, E); }
.Lmy_gb6_acq:
.Lmy_gb6_done:
.LBB0_382:
	s_or_b64 exec, exec, s[4:5]
	s_mov_b32 s101, -1
	v_mov_b32_e32 v10, v254
	s_barrier
	s_cmpk_lt_i32 s33, 0x1400
	s_nop 0
	v_readfirstlane_b32 s5, v10
	s_cbranch_scc0 .LBB0_398
	v_lshlrev_b32_e32 v0, 4, v10
	v_add_u32_e32 v1, 0x2000, v0
	v_ashrrev_i32_e32 v2, 31, v1
	v_lshrrev_b32_e32 v2, 22, v2
	v_add_u32_e32 v2, v1, v2
	v_ashrrev_i32_e32 v8, 10, v2
	v_mul_i32_i24_e32 v2, 0x400, v8
	v_sub_u32_e32 v1, v1, v2
	v_lshrrev_b32_e32 v2, 4, v1
	v_bitop3_b32 v1, v2, v1, 32 bitop3:0x6c
	v_ashrrev_i32_e32 v2, 31, v1
	v_lshrrev_b32_e32 v2, 26, v2
	v_add_u32_e32 v2, v1, v2
	v_lshlrev_b32_e32 v3, 3, v8
	v_ashrrev_i32_e32 v9, 6, v2
	v_and_b32_e32 v3, -16, v3
	v_add_u32_e32 v3, v9, v3
	v_and_b32_e32 v4, 3, v9
	s_mov_b32 s0, 0x1fffe0
	v_lshrrev_b32_e32 v5, 2, v3
	v_lshlrev_b32_e32 v6, 1, v3
	v_and_b32_e32 v2, 0xc0, v2
	v_and_or_b32 v4, v3, s0, v4
	v_and_b32_e32 v5, 4, v5
	v_and_b32_e32 v6, 24, v6
	v_sub_u32_e32 v1, v1, v2
	v_mov_b32_e32 v2, 1
	v_or3_b32 v4, v4, v5, v6
	v_lshlrev_b32_e32 v5, 5, v8
	v_ashrrev_i16_sdwa v1, v2, sext(v1) dst_sel:DWORD dst_unused:UNUSED_PAD src0_sel:DWORD src1_sel:BYTE_0
	v_and_b32_e32 v5, 32, v5
	v_bfe_i32 v11, v1, 0, 16
	v_add_lshl_u32 v1, v5, v11, 1
	v_lshl_add_u32 v128, v4, 11, v1
	v_lshl_add_u32 v130, v3, 11, v1
	v_bfe_i32 v1, v10, 27, 1
	v_lshrrev_b32_e32 v1, 22, v1
	v_add_u32_e32 v1, v0, v1
	v_and_b32_e32 v1, 0xfffffc00, v1
	v_sub_u32_e32 v0, v0, v1
	v_lshrrev_b32_e32 v1, 4, v0
	v_ashrrev_i32_e32 v3, 31, v10
	v_bitop3_b32 v0, v1, v0, 32 bitop3:0x6c
	v_lshrrev_b32_e32 v3, 26, v3
	v_ashrrev_i32_e32 v1, 31, v0
	v_add_u32_e32 v3, v10, v3
	v_lshrrev_b32_e32 v1, 26, v1
	v_ashrrev_i32_e32 v13, 6, v3
	v_add_u32_e32 v1, v0, v1
	v_lshlrev_b32_e32 v3, 3, v13
	v_ashrrev_i32_e32 v12, 6, v1
	v_and_b32_e32 v3, -16, v3
	v_add_u32_e32 v3, v12, v3
	v_and_b32_e32 v4, 3, v12
	v_and_or_b32 v4, v3, s0, v4
	s_ashr_i32 s0, s33, 31
	s_lshr_b32 s0, s0, 29
	s_add_i32 s0, s33, s0
	s_ashr_i32 s8, s5, 6
	s_ashr_i32 s1, s0, 3
	s_and_b32 s0, s0, -8
	s_ashr_i32 s10, s5, 8
	s_lshl_b32 s46, s8, 10
	s_sub_i32 s0, s33, s0
	s_cmp_lt_i32 s0, 0
	s_movk_i32 s47, 0x281
	s_cselect_b32 s4, s47, 0x280
	s_mul_i32 s0, s0, s4
	s_add_i32 s0, s0, s1
	s_ashr_i32 s1, s0, 31
	s_lshr_b32 s1, s1, 25
	s_add_i32 s1, s0, s1
	s_ashr_i32 s4, s1, 7
	s_and_b32 s1, s1, 0xff80
	s_sub_i32 s0, s0, s1
	s_bfe_i32 s1, s0, 0x80000
	s_bfe_u32 s1, s1, 0x3000c
	s_add_i32 s1, s0, s1
	s_lshl_b32 s6, s4, 3
	s_bfe_i32 s4, s1, 0x80000
	s_and_b32 s1, s1, 0xf8
	s_sub_i32 s0, s0, s1
	s_sext_i32_i16 s4, s4
	s_sext_i32_i8 s0, s0
	v_lshrrev_b32_e32 v5, 2, v3
	v_lshlrev_b32_e32 v6, 1, v3
	v_and_b32_e32 v1, 0xc0, v1
	s_lshr_b32 s4, s4, 3
	s_add_i32 s38, s6, s0
	v_and_b32_e32 v5, 4, v5
	v_and_b32_e32 v6, 24, v6
	v_sub_u32_e32 v0, v0, v1
	s_ashr_i32 s39, s38, 31
	s_bfe_i64 s[6:7], s[4:5], 0x100000
	v_or3_b32 v4, v4, v5, v6
	v_lshlrev_b32_e32 v5, 5, v13
	v_ashrrev_i16_sdwa v0, v2, sext(v0) dst_sel:DWORD dst_unused:UNUSED_PAD src0_sel:DWORD src1_sel:BYTE_0
	s_lshl_b64 s[0:1], s[38:39], 19
	s_lshl_b64 s[6:7], s[6:7], 19
	v_and_b32_e32 v5, 32, v5
	v_bfe_i32 v14, v0, 0, 16
	s_add_u32 s42, s30, s6
	v_add_lshl_u32 v0, v5, v14, 1
	s_addc_u32 s43, s31, s7
	s_add_i32 s39, s46, 0
	v_lshl_add_u32 v132, v4, 11, v0
	s_add_i32 m0, s39, 0x10000
	v_lshl_add_u32 v134, v3, 11, v0
	global_load_lds_dwordx4 v132, s[42:43]
	s_add_i32 m0, s39, 0x12000
	s_add_u32 s6, s42, 0x40000
	global_load_lds_dwordx4 v128, s[42:43]
	s_addc_u32 s7, s43, 0
	s_add_i32 m0, s39, 0x14000
	v_mov_b32_e32 v133, 0
	global_load_lds_dwordx4 v132, s[6:7]
	s_add_i32 m0, s39, 0x16000
	s_add_u32 s40, s16, s0
	s_addc_u32 s41, s17, s1
	s_add_i32 s48, s39, 0x2000
	global_load_lds_dwordx4 v128, s[6:7]
	s_mov_b32 m0, s39
	s_add_u32 s0, s40, 0x40000
	global_load_lds_dwordx4 v134, s[40:41]
	s_mov_b32 m0, s48
	s_addc_u32 s1, s41, 0
	s_add_i32 s49, s39, 0x4000
	global_load_lds_dwordx4 v130, s[40:41]
	s_mov_b32 m0, s49
	s_add_i32 s50, s39, 0x6000
	global_load_lds_dwordx4 v134, s[0:1]
	s_mov_b32 m0, s50
	v_mov_b32_e32 v129, v133
	global_load_lds_dwordx4 v130, s[0:1]
	v_mov_b32_e32 v135, v133
	v_mov_b32_e32 v131, v133
	s_cmp_eq_u32 s10, 1
	s_mov_b32 s51, 0
	v_lshl_add_u64 v[6:7], s[42:43], 0, v[132:133]
	v_lshl_add_u64 v[4:5], s[42:43], 0, v[128:129]
	v_lshl_add_u64 v[0:1], s[40:41], 0, v[134:135]
	s_cselect_b64 s[6:7], -1, 0
	s_cmp_lg_u32 s10, 1
	v_lshl_add_u64 v[2:3], s[40:41], 0, v[130:131]
	s_cbranch_scc1 .LBB0_385
	s_barrier

;     __host__ __device__ bool next(int i, Unit& u) const {
;         const long L = (long)i * G + c; if (L >= nwg) return false;
;         int wgid = (int)L; { const int q = nwg / NXCD, r = nwg % NXCD, xcd = wgid % NXCD, off = wgid / NXCD; wgid = (xcd < r ? xcd * (q + 1) : r * (q + 1) + (xcd - r) * q) + off; }
;         const int nig = WGM * nN, gid = wgid / nig, fm = gid * WGM, gsz = (nM - fm) < WGM ? (nM - fm) : WGM;
;         u.pm = fm + ((wgid % nig) % gsz); u.pn = (wgid % nig) / gsz; return true;
; __global__ void __launch_bounds__(512, 2) mk_fwd(Args a) {
;     ...
;     { pg8::Gemm g{Hb, Wdn_t, TT, DM, DFF}; pg8::StaticOrder S; S.init(TT, DM, G, vbx); pg8::EpiFinal E{out, X1B, SSQ2, bar_ctr + 1024, g_fin};
;       pg8::gemm_phase<pg8::EpiFinal, pg8::StaticOrder, true, true>(lds, g, S, E); }
.Lmy_gb7_acq:
.Lmy_gb7_done:
.LBB0_415:
	s_or_b64 exec, exec, s[0:1]
	s_barrier
	s_and_b64 vcc, exec, s[2:3]
	v_readfirstlane_b32 s0, v254
	s_cbranch_vccnz .LBB0_418
	s_lshr_b32 s1, s76, 29
	s_add_i32 s1, s33, s1
	s_ashr_i32 s4, s1, 3
	s_and_b32 s1, s1, -8
	s_sub_i32 s1, s33, s1
	s_cmp_lt_i32 s1, 0
	s_movk_i32 s5, 0xa1
	s_cselect_b32 s5, s5, 0xa0
	s_mul_i32 s1, s1, s5
	s_add_i32 s1, s1, s4
	s_ashr_i32 s4, s1, 31
	s_lshr_b32 s4, s4, 27
	s_add_i32 s4, s1, s4
	s_ashr_i32 s5, s4, 5
	s_and_b32 s4, s4, 0xffe0
	s_sub_i32 s1, s1, s4
	s_bfe_i32 s4, s1, 0x80000
	s_bfe_u32 s4, s4, 0x3000c
	s_add_i32 s4, s1, s4
	s_bfe_i32 s6, s4, 0x80000
	s_and_b32 s4, s4, 0xf8
	s_sub_i32 s1, s1, s4
	s_lshl_b32 s5, s5, 3
	s_sext_i32_i16 s6, s6
	s_sext_i32_i8 s1, s1
	s_add_i32 s38, s5, s1
	s_ashr_i32 s6, s6, 3
	s_and_b64 vcc, exec, s[2:3]
	s_cbranch_vccz .LBB0_419
